# select_row: generic threshold search now bit 31, packed digit phase 30..24, bit 23, digit phase 22..16, then bits 15..0 (digit block parametrized by shift); same threshold
# speedup vs baseline: 1.0087x; 1.0030x over previous
; DI void select_row(const float* SC, unsigned* dmask, int b, int t, int lane) {
;     ...
;     unsigned T = 0u; bool hit = false; int startbit = 31;
;     {
;         int cnt; SEL_COUNT(0xBF800000u, cnt);
;         if (cnt < 256) {
; #pragma unroll 1
;             for (unsigned e = 0x7Eu; e >= 0x7Au; --e) {
;                 const unsigned cand = 0x80000000u | (e << 23); SEL_COUNT(cand, cnt);
;                 if (cnt >= 256) { T = cand; startbit = 22; hit = (cnt == 256); break; }
;             }
;         }
;     }
;     if (!hit) {
;     ...
;             const unsigned cand = T | (1u << bit); int cnt; SEL_COUNT(cand, cnt);
;             if (cnt >= 256) { T = cand; if (cnt == 256) { hit = true; break; } }
;         }
;     }
.Lsel7:
	s_mov_b32 s84, 16
.Lsel7g:
	s_add_i32 s10, s84, 7
	s_lshl_b32 s10, 1, s10
	s_add_i32 s10, s10, -1
	s_add_u32 s10, s14, s10
	s_lshr_b32 s11, s84, 3
	s_mul_i32 s11, s11, 0x101
	s_lshl_b32 s66, s11, 16
	s_add_u32 s11, s11, 0x0c0c0400
	s_add_u32 s66, s66, 0x04000c0c
	s_mov_b32 s67, 0x80808080
	v_min_u32_e32 v182, s10, v11
	v_min_u32_e32 v183, s10, v10
	v_min_u32_e32 v184, s10, v121
	v_min_u32_e32 v185, s10, v9
	v_sub_u32_e64 v182, v182, s14 clamp
	v_sub_u32_e64 v183, v183, s14 clamp
	v_sub_u32_e64 v184, v184, s14 clamp
	v_sub_u32_e64 v185, v185, s14 clamp
	v_perm_b32 v186, v183, v182, s11
	v_perm_b32 v187, v185, v184, s66
	v_or3_b32 v174, v186, v187, s67
	v_min_u32_e32 v182, s10, v7
	v_min_u32_e32 v183, s10, v6
	v_min_u32_e32 v184, s10, v8
	v_min_u32_e32 v185, s10, v5
	v_sub_u32_e64 v182, v182, s14 clamp
	v_sub_u32_e64 v183, v183, s14 clamp
	v_sub_u32_e64 v184, v184, s14 clamp
	v_sub_u32_e64 v185, v185, s14 clamp
	v_perm_b32 v186, v183, v182, s11
	v_perm_b32 v187, v185, v184, s66
	v_or3_b32 v175, v186, v187, s67
	s_and_b64 vcc, exec, s[82:83]
	s_cbranch_vccnz .Ls7_su1
	v_min_u32_e32 v182, s10, v33
	v_min_u32_e32 v183, s10, v41
	v_min_u32_e32 v184, s10, v32
	v_min_u32_e32 v185, s10, v42
	v_sub_u32_e64 v182, v182, s14 clamp
	v_sub_u32_e64 v183, v183, s14 clamp
	v_sub_u32_e64 v184, v184, s14 clamp
	v_sub_u32_e64 v185, v185, s14 clamp
	v_perm_b32 v186, v183, v182, s11
	v_perm_b32 v187, v185, v184, s66
	v_or3_b32 v176, v186, v187, s67
	v_min_u32_e32 v182, s10, v29
	v_min_u32_e32 v183, s10, v30
	v_min_u32_e32 v184, s10, v28
	v_min_u32_e32 v185, s10, v31
	v_sub_u32_e64 v182, v182, s14 clamp
	v_sub_u32_e64 v183, v183, s14 clamp
	v_sub_u32_e64 v184, v184, s14 clamp
	v_sub_u32_e64 v185, v185, s14 clamp
	v_perm_b32 v186, v183, v182, s11
	v_perm_b32 v187, v185, v184, s66
	v_or3_b32 v177, v186, v187, s67

; DI void select_row(const float* SC, unsigned* dmask, int b, int t, int lane) {
;     ...
;     if (!hit) {
;     ...
;             const unsigned cand = T | (1u << bit); int cnt; SEL_COUNT(cand, cnt);
;             if (cnt >= 256) { T = cand; if (cnt == 256) { hit = true; break; } }
;         }
;     }
.Ls7_rej:
	s_add_i32 s57, s57, -1
	s_cmp_ge_i32 s57, 0
	s_cbranch_scc1 .Ls7_loop
	s_lshl_b32 s56, s56, s84
	s_or_b32 s14, s14, s56
	s_add_i32 s80, s84, -1
	s_cmp_eq_u32 s84, 24
	s_cselect_b32 s84, 23, 0
	s_branch .LBB0_571
.Ls7_hit:
	s_lshl_b32 s56, s56, s84
	s_or_b32 s14, s14, s56
	v_mov_b32_e32 v2, s14
	s_mov_b64 s[8:9], -1
	s_branch .LBB0_582
.LBB0_570:
	s_mov_b32 s84, 31
	s_mov_b32 s80, 31
	s_mov_b32 s14, 0
	s_mov_b64 s[8:9], -1
	v_mov_b32_e32 v2, s14

; DI void select_row(const float* SC, unsigned* dmask, int b, int t, int lane) {
;     ...
;     if (!hit) {
;     ...
;             const unsigned cand = T | (1u << bit); int cnt; SEL_COUNT(cand, cnt);
;             if (cnt >= 256) { T = cand; if (cnt == 256) { hit = true; break; } }
;         }
;     }
.Lsel_rej:
	s_add_i32 s57, s57, -1
	s_cmp_ge_i32 s57, s84
	s_cbranch_scc1 .LBB0_574
	s_cmp_eq_u32 s84, 0
	s_cbranch_scc1 .Lsel_fin
	s_mov_b32 s14, s56
	s_add_i32 s84, s84, -7
	s_branch .Lsel7g
.Lsel_fin:
	v_mov_b32_e32 v2, s56
	s_branch .LBB0_582
